# mix queue: XCD slice chosen by blockIdx&7, each workgroup's first ticket is static (blockIdx>>3), later tickets from the per-XCD counter
# speedup vs baseline: 1.0012x; 1.0012x over previous
.LBB0_633:
	s_or_b64 exec, exec, s[36:37]
	s_lshl_b32 s70, s14, 6
	s_lshl_b64 s[20:21], s[70:71], 2
	s_add_u32 s15, s30, s20
	s_addc_u32 s16, s31, s21
	s_add_u32 s20, s15, 0xf79f700
	s_waitcnt lgkmcnt(0)
	v_cvt_f32_u32_e32 v0, s14
	s_addc_u32 s21, s16, 0
	s_and_b32 s100, s2, 7
	s_nop 0
	s_lshl_b32 s101, s100, 5
	s_add_u32 s20, s20, s101
	s_addc_u32 s21, s21, 0
	v_writelane_b32 v254, s100, 0
	s_lshr_b32 s101, s2, 3
	s_add_i32 s101, s101, 1
	v_writelane_b32 v254, s101, 1
	v_writelane_b32 v251, s20, 37
	v_writelane_b32 v253, s84, 10
	s_movk_i32 s15, 0xbc
	v_writelane_b32 v251, s21, 38
	s_and_b64 s[20:21], s[84:85], exec
	s_cselect_b32 s15, s15, 0x78
	s_lshl_b32 s16, s14, 16
	v_mul_f32_e32 v0, 0xbe99999a, v0
	v_writelane_b32 v251, s16, 39
	v_mul_f32_e32 v1, 0x3fb8aa3b, v0
	s_mov_b32 s16, 0x3fb8aa3b
	v_fma_f32 v2, v0, s16, -v1
	v_rndne_f32_e32 v3, v1
	v_fmac_f32_e32 v2, 0x32a5705f, v0
	v_sub_f32_e32 v1, v1, v3
	v_add_f32_e32 v1, v1, v2
	v_exp_f32_e32 v1, v1
	v_cvt_i32_f32_e32 v2, v3
	s_lshl_b32 s16, s14, 2
	v_writelane_b32 v251, s16, 40
	s_mov_b32 s16, 0xc2ce8ed0
	v_ldexp_f32 v1, v1, v2
	v_cmp_ngt_f32_e32 vcc, s16, v0
	s_mov_b32 s16, 0x42b17218
	s_lshl_b32 s38, s14, 9
	v_cndmask_b32_e32 v1, 0, v1, vcc
	v_cmp_nlt_f32_e32 vcc, s16, v0
	s_lshl_b32 s16, s14, 7
	v_writelane_b32 v251, s16, 41
	s_lshl_b32 s19, s14, 18
	v_writelane_b32 v251, s19, 42
	s_mov_b32 s40, s38
	v_writelane_b32 v253, s85, 11
	v_writelane_b32 v251, s40, 43
	s_mov_b32 s39, s71
	s_lshl_b32 s74, s14, 10
	v_writelane_b32 v251, s41, 44
	v_readlane_b32 s40, v253, 12
	s_lshl_b32 s70, s14, 8
	s_or_b32 s16, s74, 0x200
	s_lshl_b32 s36, s14, 6
	s_lshl_b64 s[38:39], s[38:39], 2
	v_readlane_b32 s48, v253, 20
	v_readlane_b32 s49, v253, 21
	s_add_u32 s19, s48, s38
	v_readlane_b32 s50, v253, 22
	v_writelane_b32 v251, s19, 45
	s_addc_u32 s19, s49, s39
	s_lshl_b64 s[38:39], s[70:71], 2
	s_mul_i32 s20, s14, 0x1200
	s_mov_b32 s21, s71
	v_readlane_b32 s51, v253, 23
	s_add_u32 s38, s50, s38
	v_readlane_b32 s54, v253, 26
	s_addc_u32 s39, s51, s39
	s_lshl_b64 s[20:21], s[20:21], 2
	s_mul_i32 s22, s14, 0x600
	s_mov_b32 s23, s71
	v_readlane_b32 s55, v253, 27
	s_add_u32 s80, s54, s20
	s_addc_u32 s81, s55, s21
	s_lshl_b64 s[20:21], s[22:23], 2
	s_mov_b32 s37, s71
	v_writelane_b32 v251, s19, 46
	s_add_u32 s82, s12, s20
	v_writelane_b32 v251, s38, 47
	s_addc_u32 s83, s13, s21
	s_lshl_b64 s[20:21], s[36:37], 2
	v_readlane_b32 s19, v252, 53
	v_writelane_b32 v251, s39, 48
	s_add_u32 s19, s19, s20
	v_writelane_b32 v251, s19, 49
	v_readlane_b32 s19, v252, 54
	s_addc_u32 s19, s19, s21
	s_add_u32 s17, s17, 0x1800000
	v_writelane_b32 v251, s19, 50
	v_writelane_b32 v251, s17, 51
	s_addc_u32 s17, s18, 0
	v_writelane_b32 v251, s17, 52
	v_readfirstlane_b32 s17, v188
	s_lshr_b32 s18, s17, 8
	s_mul_i32 s17, s18, 0x12000
	s_add_i32 s17, s17, 0
	v_writelane_b32 v251, s18, 53
	s_addk_i32 s18, 0xff80
	v_writelane_b32 v251, s18, 54
	s_add_i32 s18, s17, 0x8800
	v_writelane_b32 v251, s18, 55
	s_add_i32 s18, s17, 0x4400
	v_writelane_b32 v251, s18, 56
	s_add_i32 s18, s17, 0x800
	v_writelane_b32 v251, s18, 57
	s_mul_i32 s19, s14, 0x1a00000
	v_readlane_b32 s20, v251, 32
	s_add_u32 s19, s20, s19
	v_cndmask_b32_e32 v0, v200, v1, vcc
	v_writelane_b32 v251, s19, 58
	v_fmamk_f32 v150, v0, 0xbf19999a, v192
	s_mul_hi_u32 s18, s14, 0x1a00000
	v_readlane_b32 s19, v251, 33
	v_sub_f32_e32 v203, 1.0, v150
	s_mov_b32 s75, s71
	s_addc_u32 s18, s19, s18
	s_barrier
	v_readlane_b32 s41, v253, 13
	v_readlane_b32 s42, v253, 14
	v_readlane_b32 s43, v253, 15
	v_readlane_b32 s44, v253, 16
	v_readlane_b32 s45, v253, 17
	v_readlane_b32 s46, v253, 18
	v_readlane_b32 s47, v253, 19
	v_readlane_b32 s52, v253, 24
	v_readlane_b32 s53, v253, 25
	v_writelane_b32 v251, s18, 59
	s_branch .LBB0_637

.LBB0_637:
	s_barrier
	v_readlane_b32 s100, v254, 1
	s_nop 3
	s_cmp_eq_u32 s100, 0
	s_cbranch_scc1 .Lq_dyn
	s_mov_b32 s101, 0
	v_writelane_b32 v254, s101, 1
	s_add_i32 s100, s100, -1
	s_and_saveexec_b64 s[36:37], s[62:63]
	v_mov_b32_e32 v1, s1
	v_mov_b32_e32 v0, s100
	s_nop 0
	ds_write_b32 v1, v0
	s_branch .LBB0_641
.Lq_dyn:
	s_and_saveexec_b64 s[36:37], s[62:63]
	s_cbranch_execz .LBB0_641
	s_mov_b64 s[40:41], exec
	v_mbcnt_lo_u32_b32 v0, s40, 0
	v_mbcnt_hi_u32_b32 v0, s41, v0
	v_cmp_eq_u32_e32 vcc, 0, v0
	s_and_saveexec_b64 s[38:39], vcc
	s_cbranch_execz .LBB0_640
	s_bcnt1_i32_b64 s18, s[40:41]
	v_mov_b32_e32 v1, s18
	v_readlane_b32 s18, v251, 37
	v_readlane_b32 s19, v251, 38
	s_nop 4
	global_atomic_add v1, v161, v1, s[18:19] sc0
.LBB0_640:
	s_or_b64 exec, exec, s[38:39]
	s_waitcnt vmcnt(0)
	v_readfirstlane_b32 s18, v1
	v_mov_b32_e32 v1, s1
	s_nop 0
	s_add_i32 s18, s18, 32
	v_add_u32_e32 v0, s18, v0
	ds_write_b32 v1, v0
